# pksplit
# speedup vs baseline: 1.0103x; 1.0074x over previous
; #define LAS __attribute__((address_space(3)))
; __device__ __forceinline__ void attn_passes(const Params& p, LAS unsigned char* lds) {
;     ...
;                 const int k = 4 * n + (w >> 1) + j;
;                 LAS unsigned char* kb = lds + (k & 7) * 16384; LAS unsigned char* vb = kb + 8192;
;                 const int lb = Ls - 128 + 32 * k;
;                 bf16x8 kf[8]; s16x4 t0[8], t1[8];
;                 { const unsigned kbo = (unsigned)(size_t)kb;
;                   const unsigned k0 = kbo + koff[0], k1 = kbo + koff[1], k2 = kbo + koff[2], k3 = kbo + koff[3], k4 = kbo + koff[4], k5 = kbo + koff[5], k6 = kbo + koff[6], k7 = kbo + koff[7];
;                   asm volatile("ds_read_b128 %0, %8\n\tds_read_b128 %1, %9\n\tds_read_b128 %2, %10\n\tds_read_b128 %3, %11\n\tds_read_b128 %4, %12\n\tds_read_b128 %5, %13\n\tds_read_b128 %6, %14\n\tds_read_b128 %7, %15"
;                                : "=&v"(kf[0]), "=&v"(kf[4]), "=&v"(kf[1]), "=&v"(kf[5]), "=&v"(kf[2]), "=&v"(kf[6]), "=&v"(kf[3]), "=&v"(kf[7])
;                                : "v"(k0), "v"(k4), "v"(k1), "v"(k5), "v"(k2), "v"(k6), "v"(k3), "v"(k7) : "memory"); }
;                 const unsigned vbo = (unsigned)(size_t)vb;
;     ...
;                 TR_BATCH(0);
;                 asm volatile("s_waitcnt lgkmcnt(8)" : "+v"(kf[0]), "+v"(kf[1]), "+v"(kf[2]), "+v"(kf[3]), "+v"(kf[4]), "+v"(kf[5]), "+v"(kf[6]), "+v"(kf[7]) :: "memory");
;                 f32x4 s1 = (f32x4){0.f, 0.f, 0.f, 0.f}, s2 = s1;
; #pragma unroll
;                 for (int ks = 0; ks < 4; ++ks) {
;                     s1 = __builtin_amdgcn_mfma_f32_16x16x32_bf16(kf[ks], qf[ks], s1, 0, 0, 0); s2 = __builtin_amdgcn_mfma_f32_16x16x32_bf16(kf[4 + ks], qf[ks], s2, 0, 0, 0); }
;                 TR_BATCH(1);
;     ...
;                 const int rel0 = lq - lb - 8 * g;
;                 const float bias0 = -sd * (float)rel0;
;                 float sv[8];
;                 if (j >= 1 && j <= 3 && lb >= 0) {
; #pragma unroll
;                     for (int jj = 0; jj < 8; ++jj) { const float raw = jj < 4 ? s1[jj & 3] : s2[jj & 3]; sv[jj] = raw * sc2 + (bias0 + sd * (float)jj); }
.LBB0_265:
	s_add_i32 s6, s93, 0xfffd8000
	s_and_b32 s6, s6, 0x1c000
	s_add_i32 s6, s6, 0
	s_add_i32 s7, s6, 0x2000
	v_add_u32_e32 v49, s6, v135
	v_add_u32_e32 v50, s6, v139
	v_add_u32_e32 v51, s6, v174
	v_add_u32_e32 v52, s6, v176
	v_add_u32_e32 v53, s6, v137
	v_add_u32_e32 v58, s6, v141
	v_add_u32_e32 v59, s6, v175
	v_add_u32_e32 v60, s6, v177
	ds_read_b128 v[54:57], v49
	ds_read_b128 v[82:85], v53
	ds_read_b128 v[62:65], v50
	ds_read_b128 v[86:89], v58
	ds_read_b128 v[74:77], v51
	ds_read_b128 v[216:219], v59
	ds_read_b128 v[78:81], v52
	ds_read_b128 v[220:223], v60
	v_add_u32_e32 v49, s7, v178
	v_add_u32_e32 v162, s7, v179
	v_add_u32_e32 v163, s7, v181
	v_add_u32_e32 v224, s7, v188
	v_add_u32_e32 v225, s7, v182
	v_add_u32_e32 v226, s7, v189
	v_add_u32_e32 v227, s7, v183
	v_add_u32_e32 v228, s7, v190
	ds_read_b64_tr_b16 v[70:71], v49
	ds_read_b64_tr_b16 v[72:73], v162
	ds_read_b64_tr_b16 v[66:67], v163
	ds_read_b64_tr_b16 v[68:69], v224
	ds_read_b64_tr_b16 v[58:59], v225
	ds_read_b64_tr_b16 v[60:61], v226
	ds_read_b64_tr_b16 v[50:51], v227
	ds_read_b64_tr_b16 v[52:53], v228
	s_waitcnt lgkmcnt(8)
	v_add_u32_e32 v49, s7, v184
	v_mfma_f32_16x16x32_bf16 v[54:57], v[54:57], v[12:15], 0
	v_add_u32_e32 v162, s7, v191
	v_add_u32_e32 v163, s7, v185
	s_add_i32 s6, s92, 0xffffffa0
	v_mfma_f32_16x16x32_bf16 v[82:85], v[82:85], v[12:15], 0
	s_cmp_lt_i32 s6, 0
	v_mfma_f32_16x16x32_bf16 v[54:57], v[62:65], v[8:11], v[54:57]
	v_mfma_f32_16x16x32_bf16 v[62:65], v[86:89], v[8:11], v[82:85]
	v_mfma_f32_16x16x32_bf16 v[54:57], v[74:77], v[4:7], v[54:57]
	v_mfma_f32_16x16x32_bf16 v[62:65], v[216:219], v[4:7], v[62:65]
	v_add_u32_e32 v216, s7, v192
	v_add_u32_e32 v217, s7, v186
	v_add_u32_e32 v218, s7, v193
	v_mfma_f32_16x16x32_bf16 v[86:89], v[78:81], v[0:3], v[54:57]
	v_add_u32_e32 v219, s7, v187
	v_mfma_f32_16x16x32_bf16 v[82:85], v[220:223], v[0:3], v[62:65]
	v_add_u32_e32 v220, s7, v194
	ds_read_b64_tr_b16 v[78:79], v49
	ds_read_b64_tr_b16 v[80:81], v162
	ds_read_b64_tr_b16 v[74:75], v163
	ds_read_b64_tr_b16 v[76:77], v216
	ds_read_b64_tr_b16 v[62:63], v217
	ds_read_b64_tr_b16 v[64:65], v218
	ds_read_b64_tr_b16 v[54:55], v219
	ds_read_b64_tr_b16 v[56:57], v220
	s_cbranch_scc1 .LBB0_267
	v_add_u32_e32 v49, 0x60, v208
	v_cvt_f32_i32_e32 v49, v49
	v_mul_f32_e64 v216, -v111, v49
	v_add_f32_e32 v162, v110, v216
	v_add_f32_e32 v163, v111, v216
	v_add_f32_e32 v220, v114, v216
	v_add_f32_e32 v221, v115, v216
	v_add_f32_e32 v218, v112, v216
	v_add_f32_e32 v219, v113, v216
	v_fma_f32 v162, v86, s36, v162
	v_fma_f32 v163, v87, s36, v163
	v_fma_f32 v86, v82, s36, v220
	v_fma_f32 v87, v83, s36, v221
	v_add_f32_e32 v82, v116, v216
	v_add_f32_e32 v83, v117, v216
	v_fma_f32 v88, v88, s36, v218
	v_fma_f32 v89, v89, s36, v219
	v_fma_f32 v82, v84, s36, v82
	v_fma_f32 v83, v85, s36, v83
	s_branch .LBB0_268

; #define LAS __attribute__((address_space(3)))
; __device__ __forceinline__ void attn_passes(const Params& p, LAS unsigned char* lds) {
;     ...
;                 const int k = 4 * n + (w >> 1) + j;
;                 LAS unsigned char* kb = lds + (k & 7) * 16384; LAS unsigned char* vb = kb + 8192;
;                 const int lb = Ls - 128 + 32 * k;
;                 bf16x8 kf[8]; s16x4 t0[8], t1[8];
;                 { const unsigned kbo = (unsigned)(size_t)kb;
;                   const unsigned k0 = kbo + koff[0], k1 = kbo + koff[1], k2 = kbo + koff[2], k3 = kbo + koff[3], k4 = kbo + koff[4], k5 = kbo + koff[5], k6 = kbo + koff[6], k7 = kbo + koff[7];
;                   asm volatile("ds_read_b128 %0, %8\n\tds_read_b128 %1, %9\n\tds_read_b128 %2, %10\n\tds_read_b128 %3, %11\n\tds_read_b128 %4, %12\n\tds_read_b128 %5, %13\n\tds_read_b128 %6, %14\n\tds_read_b128 %7, %15"
;                                : "=&v"(kf[0]), "=&v"(kf[4]), "=&v"(kf[1]), "=&v"(kf[5]), "=&v"(kf[2]), "=&v"(kf[6]), "=&v"(kf[3]), "=&v"(kf[7])
;                                : "v"(k0), "v"(k4), "v"(k1), "v"(k5), "v"(k2), "v"(k6), "v"(k3), "v"(k7) : "memory"); }
;                 const unsigned vbo = (unsigned)(size_t)vb;
;     ...
;                 TR_BATCH(0);
;                 asm volatile("s_waitcnt lgkmcnt(8)" : "+v"(kf[0]), "+v"(kf[1]), "+v"(kf[2]), "+v"(kf[3]), "+v"(kf[4]), "+v"(kf[5]), "+v"(kf[6]), "+v"(kf[7]) :: "memory");
;                 f32x4 s1 = (f32x4){0.f, 0.f, 0.f, 0.f}, s2 = s1;
; #pragma unroll
;                 for (int ks = 0; ks < 4; ++ks) {
;                     s1 = __builtin_amdgcn_mfma_f32_16x16x32_bf16(kf[ks], qf[ks], s1, 0, 0, 0); s2 = __builtin_amdgcn_mfma_f32_16x16x32_bf16(kf[4 + ks], qf[ks], s2, 0, 0, 0); }
;                 TR_BATCH(1);
;     ...
;                 const int rel0 = lq - lb - 8 * g;
;                 const float bias0 = -sd * (float)rel0;
;                 float sv[8];
;                 if (j >= 1 && j <= 3 && lb >= 0) {
; #pragma unroll
;                     for (int jj = 0; jj < 8; ++jj) { const float raw = jj < 4 ? s1[jj & 3] : s2[jj & 3]; sv[jj] = raw * sc2 + (bias0 + sd * (float)jj); }
.LBB0_280:
	s_add_i32 s12, s93, 0xfffdc000
	s_and_b32 s12, s12, 0x1c000
	s_add_i32 s12, s12, 0
	s_add_i32 s13, s12, 0x2000
	v_add_u32_e32 v48, s12, v135
	v_add_u32_e32 v49, s12, v139
	v_add_u32_e32 v50, s12, v174
	v_add_u32_e32 v51, s12, v176
	v_add_u32_e32 v56, s12, v137
	v_add_u32_e32 v57, s12, v141
	v_add_u32_e32 v58, s12, v175
	v_add_u32_e32 v59, s12, v177
	ds_read_b128 v[52:55], v48
	ds_read_b128 v[80:83], v56
	ds_read_b128 v[64:67], v49
	ds_read_b128 v[84:87], v57
	ds_read_b128 v[72:75], v50
	ds_read_b128 v[216:219], v58
	ds_read_b128 v[76:79], v51
	ds_read_b128 v[220:223], v59
	v_add_u32_e32 v88, s13, v178
	v_add_u32_e32 v89, s13, v179
	v_add_u32_e32 v215, s13, v181
	v_add_u32_e32 v224, s13, v188
	v_add_u32_e32 v225, s13, v182
	v_add_u32_e32 v226, s13, v189
	v_add_u32_e32 v227, s13, v183
	v_add_u32_e32 v228, s13, v190
	ds_read_b64_tr_b16 v[68:69], v88
	ds_read_b64_tr_b16 v[70:71], v89
	ds_read_b64_tr_b16 v[60:61], v215
	ds_read_b64_tr_b16 v[62:63], v224
	ds_read_b64_tr_b16 v[56:57], v225
	ds_read_b64_tr_b16 v[58:59], v226
	ds_read_b64_tr_b16 v[48:49], v227
	ds_read_b64_tr_b16 v[50:51], v228
	s_waitcnt lgkmcnt(8)
	v_add_u32_e32 v88, s13, v184
	v_mfma_f32_16x16x32_bf16 v[52:55], v[52:55], v[12:15], 0
	v_add_u32_e32 v89, s13, v191
	v_add_u32_e32 v215, s13, v185
	s_sub_i32 s12, s92, 64
	v_mfma_f32_16x16x32_bf16 v[80:83], v[80:83], v[12:15], 0
	s_cmp_lt_i32 s12, 0
	v_mfma_f32_16x16x32_bf16 v[52:55], v[64:67], v[8:11], v[52:55]
	v_mfma_f32_16x16x32_bf16 v[64:67], v[84:87], v[8:11], v[80:83]
	v_mfma_f32_16x16x32_bf16 v[52:55], v[72:75], v[4:7], v[52:55]
	v_mfma_f32_16x16x32_bf16 v[64:67], v[216:219], v[4:7], v[64:67]
	v_add_u32_e32 v216, s13, v192
	v_add_u32_e32 v217, s13, v186
	v_add_u32_e32 v218, s13, v193
	v_mfma_f32_16x16x32_bf16 v[84:87], v[76:79], v[0:3], v[52:55]
	v_add_u32_e32 v219, s13, v187
	v_mfma_f32_16x16x32_bf16 v[80:83], v[220:223], v[0:3], v[64:67]
	v_add_u32_e32 v220, s13, v194
	ds_read_b64_tr_b16 v[76:77], v88
	ds_read_b64_tr_b16 v[78:79], v89
	ds_read_b64_tr_b16 v[72:73], v215
	ds_read_b64_tr_b16 v[74:75], v216
	ds_read_b64_tr_b16 v[64:65], v217
	ds_read_b64_tr_b16 v[66:67], v218
	ds_read_b64_tr_b16 v[52:53], v219
	ds_read_b64_tr_b16 v[54:55], v220
	s_cbranch_scc1 .LBB0_282
	v_add_u32_e32 v88, 64, v208
	v_cvt_f32_i32_e32 v88, v88
	v_mul_f32_e64 v216, -v111, v88
	v_add_f32_e32 v88, v110, v216
	v_add_f32_e32 v89, v111, v216
	v_add_f32_e32 v220, v114, v216
	v_add_f32_e32 v221, v115, v216
	v_add_f32_e32 v218, v112, v216
	v_add_f32_e32 v219, v113, v216
	v_fma_f32 v88, v84, s36, v88
	v_fma_f32 v89, v85, s36, v89
	v_fma_f32 v84, v80, s36, v220
	v_fma_f32 v85, v81, s36, v221
	v_add_f32_e32 v80, v116, v216
	v_add_f32_e32 v81, v117, v216
	v_fma_f32 v86, v86, s36, v218
	v_fma_f32 v87, v87, s36, v219
	v_fma_f32 v80, v82, s36, v80
	v_fma_f32 v81, v83, s36, v81
	s_branch .LBB0_283

; #define LAS __attribute__((address_space(3)))
; __device__ __forceinline__ void attn_passes(const Params& p, LAS unsigned char* lds) {
;     ...
;                 const int k = 4 * n + (w >> 1) + j;
;                 LAS unsigned char* kb = lds + (k & 7) * 16384; LAS unsigned char* vb = kb + 8192;
;                 const int lb = Ls - 128 + 32 * k;
;                 bf16x8 kf[8]; s16x4 t0[8], t1[8];
;                 { const unsigned kbo = (unsigned)(size_t)kb;
;                   const unsigned k0 = kbo + koff[0], k1 = kbo + koff[1], k2 = kbo + koff[2], k3 = kbo + koff[3], k4 = kbo + koff[4], k5 = kbo + koff[5], k6 = kbo + koff[6], k7 = kbo + koff[7];
;                   asm volatile("ds_read_b128 %0, %8\n\tds_read_b128 %1, %9\n\tds_read_b128 %2, %10\n\tds_read_b128 %3, %11\n\tds_read_b128 %4, %12\n\tds_read_b128 %5, %13\n\tds_read_b128 %6, %14\n\tds_read_b128 %7, %15"
;                                : "=&v"(kf[0]), "=&v"(kf[4]), "=&v"(kf[1]), "=&v"(kf[5]), "=&v"(kf[2]), "=&v"(kf[6]), "=&v"(kf[3]), "=&v"(kf[7])
;                                : "v"(k0), "v"(k4), "v"(k1), "v"(k5), "v"(k2), "v"(k6), "v"(k3), "v"(k7) : "memory"); }
;                 const unsigned vbo = (unsigned)(size_t)vb;
;     ...
;                 TR_BATCH(0);
;                 asm volatile("s_waitcnt lgkmcnt(8)" : "+v"(kf[0]), "+v"(kf[1]), "+v"(kf[2]), "+v"(kf[3]), "+v"(kf[4]), "+v"(kf[5]), "+v"(kf[6]), "+v"(kf[7]) :: "memory");
;                 f32x4 s1 = (f32x4){0.f, 0.f, 0.f, 0.f}, s2 = s1;
; #pragma unroll
;                 for (int ks = 0; ks < 4; ++ks) {
;                     s1 = __builtin_amdgcn_mfma_f32_16x16x32_bf16(kf[ks], qf[ks], s1, 0, 0, 0); s2 = __builtin_amdgcn_mfma_f32_16x16x32_bf16(kf[4 + ks], qf[ks], s2, 0, 0, 0); }
;                 TR_BATCH(1);
;     ...
;                 const int rel0 = lq - lb - 8 * g;
;                 const float bias0 = -sd * (float)rel0;
;                 float sv[8];
;                 if (j >= 1 && j <= 3 && lb >= 0) {
; #pragma unroll
;                     for (int jj = 0; jj < 8; ++jj) { const float raw = jj < 4 ? s1[jj & 3] : s2[jj & 3]; sv[jj] = raw * sc2 + (bias0 + sd * (float)jj); }
.LBB0_295:
	s_add_i32 s52, s93, 0xfffe0000
	s_and_b32 s52, s52, 0x1c000
	s_add_i32 s52, s52, 0
	s_add_i32 s53, s52, 0x2000
	v_add_u32_e32 v48, s52, v135
	v_add_u32_e32 v49, s52, v139
	v_add_u32_e32 v50, s52, v174
	v_add_u32_e32 v51, s52, v176
	v_add_u32_e32 v52, s52, v137
	v_add_u32_e32 v53, s52, v141
	v_add_u32_e32 v54, s52, v175
	v_add_u32_e32 v55, s52, v177
	ds_read_b128 v[56:59], v48
	ds_read_b128 v[80:83], v52
	ds_read_b128 v[64:67], v49
	ds_read_b128 v[84:87], v53
	ds_read_b128 v[72:75], v50
	ds_read_b128 v[216:219], v54
	ds_read_b128 v[76:79], v51
	ds_read_b128 v[220:223], v55
	v_add_u32_e32 v88, s53, v178
	v_add_u32_e32 v89, s53, v179
	v_add_u32_e32 v215, s53, v181
	v_add_u32_e32 v224, s53, v188
	v_add_u32_e32 v225, s53, v182
	v_add_u32_e32 v226, s53, v189
	v_add_u32_e32 v227, s53, v183
	v_add_u32_e32 v228, s53, v190
	ds_read_b64_tr_b16 v[68:69], v88
	ds_read_b64_tr_b16 v[70:71], v89
	ds_read_b64_tr_b16 v[60:61], v215
	ds_read_b64_tr_b16 v[62:63], v224
	ds_read_b64_tr_b16 v[52:53], v225
	ds_read_b64_tr_b16 v[54:55], v226
	ds_read_b64_tr_b16 v[48:49], v227
	ds_read_b64_tr_b16 v[50:51], v228
	s_waitcnt lgkmcnt(8)
	v_add_u32_e32 v88, s53, v184
	v_mfma_f32_16x16x32_bf16 v[56:59], v[56:59], v[12:15], 0
	v_add_u32_e32 v89, s53, v191
	v_add_u32_e32 v215, s53, v185
	s_sub_i32 s52, s92, 32
	v_mfma_f32_16x16x32_bf16 v[80:83], v[80:83], v[12:15], 0
	s_cmp_lt_i32 s52, 0
	v_mfma_f32_16x16x32_bf16 v[56:59], v[64:67], v[8:11], v[56:59]
	v_mfma_f32_16x16x32_bf16 v[64:67], v[84:87], v[8:11], v[80:83]
	v_mfma_f32_16x16x32_bf16 v[56:59], v[72:75], v[4:7], v[56:59]
	v_mfma_f32_16x16x32_bf16 v[64:67], v[216:219], v[4:7], v[64:67]
	v_add_u32_e32 v216, s53, v192
	v_add_u32_e32 v217, s53, v186
	v_add_u32_e32 v218, s53, v193
	v_mfma_f32_16x16x32_bf16 v[84:87], v[76:79], v[0:3], v[56:59]
	v_add_u32_e32 v219, s53, v187
	v_mfma_f32_16x16x32_bf16 v[80:83], v[220:223], v[0:3], v[64:67]
	v_add_u32_e32 v220, s53, v194
	ds_read_b64_tr_b16 v[76:77], v88
	ds_read_b64_tr_b16 v[78:79], v89
	ds_read_b64_tr_b16 v[72:73], v215
	ds_read_b64_tr_b16 v[74:75], v216
	ds_read_b64_tr_b16 v[64:65], v217
	ds_read_b64_tr_b16 v[66:67], v218
	ds_read_b64_tr_b16 v[56:57], v219
	ds_read_b64_tr_b16 v[58:59], v220
	s_cbranch_scc1 .LBB0_297
	v_add_u32_e32 v88, 32, v208
	v_cvt_f32_i32_e32 v88, v88
	v_mul_f32_e64 v216, -v111, v88
	v_add_f32_e32 v88, v110, v216
	v_add_f32_e32 v89, v111, v216
	v_add_f32_e32 v220, v114, v216
	v_add_f32_e32 v221, v115, v216
	v_add_f32_e32 v218, v112, v216
	v_add_f32_e32 v219, v113, v216
	v_fma_f32 v88, v84, s36, v88
	v_fma_f32 v89, v85, s36, v89
	v_fma_f32 v84, v80, s36, v220
	v_fma_f32 v85, v81, s36, v221
	v_add_f32_e32 v80, v116, v216
	v_add_f32_e32 v81, v117, v216
	v_fma_f32 v86, v86, s36, v218
	v_fma_f32 v87, v87, s36, v219
	v_fma_f32 v80, v82, s36, v80
	v_fma_f32 v81, v83, s36, v81
	s_branch .LBB0_298
